# grid barrier: release side polls the top-level arrival counter directly (no relay stage); L1 invalidate issued at arrival by a second wave
# speedup vs baseline: 1.0459x; 1.0092x over previous
; #define LAS __attribute__((address_space(3)))
; DI unsigned xb_xcc_id() { return (unsigned)__builtin_amdgcn_s_getreg((3 << 11) | 20) & 0xFu; }
; DI void xcd_barrier(unsigned* bar, volatile LAS unsigned* st, const int tid) {
;     asm volatile("s_waitcnt vmcnt(0)" ::: "memory");
;     __syncthreads();
;     if (tid == 0) {
;         const unsigned x = xb_xcc_id();
;         __builtin_amdgcn_s_waitcnt(0);
;         unsigned nloc = st[0], nx = st[1];
;         if (nloc == 0u) { xcd_barrier_complete(bar, x, nloc, nx); st[0] = nloc; st[1] = nx; }
.LBB0_26:
	s_mov_b32 s83, s24
	s_mov_b32 s18, s85
	v_mov_b32_e32 v174, v251
	s_andn2_b64 vcc, exec, s[2:3]
	s_cbranch_vccnz .LBB0_80
	s_waitcnt vmcnt(0)
	v_cmp_eq_u32_e32 vcc, 0, v174
	s_barrier
	v_cmp_eq_u32_e64 s[2:3], 64, v174
	s_and_saveexec_b64 s[4:5], s[2:3]
	s_cbranch_execz .Lxb_noinv
	buffer_inv sc1
	s_waitcnt vmcnt(0)
.Lxb_noinv:
	s_mov_b64 exec, s[4:5]
	s_and_saveexec_b64 s[0:1], vcc
	s_cbranch_execz .LBB0_79
	v_readlane_b32 s3, v255, 0
	s_getreg_b32 s2, hwreg(HW_REG_XCC_ID, 0, 4)
	s_waitcnt vmcnt(0) expcnt(0) lgkmcnt(0)
	v_mov_b32_e32 v0, s3
	ds_read_b32 v2, v0
	v_readlane_b32 s3, v255, 1
	s_and_b32 s8, s2, 15
	s_waitcnt lgkmcnt(0)
	v_cmp_ne_u32_e32 vcc, 0, v2
	v_mov_b32_e32 v0, s3
	ds_read_b32 v0, v0
	s_cbranch_vccnz .LBB0_43
	s_mov_b32 s9, 1
	s_branch .LBB0_31

; DI unsigned xb_ld(unsigned* p)              { return __hip_atomic_load(p, __ATOMIC_RELAXED, __HIP_MEMORY_SCOPE_AGENT); }
; DI unsigned xb_add(unsigned* p, unsigned v) { return __hip_atomic_fetch_add(p, v, __ATOMIC_RELAXED, __HIP_MEMORY_SCOPE_AGENT); }
; #define XB_SPIN(cond, bar) do { unsigned _sp = 0; while (cond) { __builtin_amdgcn_s_sleep(1); \
;     if ((++_sp & 255u) == 0u) { if (xb_ld(&(bar)[XB_TMO])) break; if (_sp > XB_SPIN_CAP) { atomicAdd(&(bar)[XB_TMO], 1u); break; } } } } while (0)
; DI void xcd_barrier(unsigned* bar, volatile LAS unsigned* st, const int tid) {
;     ...
;         const unsigned old = xb_add(&bar[XB_XSUB(x)], 1u);
;         const unsigned gen = old / nloc;
;         if (old + 1u == (gen + 1u) * nloc) {
;             __builtin_amdgcn_fence(__ATOMIC_RELEASE, "agent");
;             asm volatile("s_waitcnt vmcnt(0)" ::: "memory");
;             const unsigned og = xb_add(&bar[XB_TOP], 1u);
;             const unsigned tg = og / nx;
;             if (og + 1u == (tg + 1u) * nx) xb_add(&bar[XB_TOPGEN], 1u);
;             else XB_SPIN(xb_ld(&bar[XB_TOPGEN]) == tg, bar);
;             __builtin_amdgcn_fence(__ATOMIC_ACQUIRE, "agent");
;             xb_add(&bar[XB_XGEN(x)], 1u);
;             asm volatile("s_waitcnt vmcnt(0)" ::: "memory");
;         } else {
;             XB_SPIN(xb_ld(&bar[XB_XGEN(x)]) == gen, bar);
;             __builtin_amdgcn_fence(__ATOMIC_ACQUIRE, "agent");
;             asm volatile("s_waitcnt vmcnt(0)" ::: "memory");
;         }
.LBB0_45:
	s_or_b64 exec, exec, s[6:7]
	v_cvt_f32_u32_e32 v4, v2
	s_waitcnt vmcnt(0)
	v_readfirstlane_b32 s4, v3
	v_sub_u32_e32 v3, 0, v2
	v_rcp_iflag_f32_e32 v4, v4
	v_add_u32_e32 v5, s4, v1
	v_mul_f32_e32 v4, 0x4f7ffffe, v4
	v_cvt_u32_f32_e32 v4, v4
	v_mul_lo_u32 v1, v3, v4
	v_mul_hi_u32 v1, v4, v1
	v_add_u32_e32 v1, v4, v1
	v_mul_hi_u32 v1, v5, v1
	v_mul_lo_u32 v3, v1, v2
	v_sub_u32_e32 v3, v5, v3
	v_add_u32_e32 v4, 1, v1
	v_cmp_ge_u32_e32 vcc, v3, v2
	s_nop 1
	v_cndmask_b32_e32 v1, v1, v4, vcc
	v_sub_u32_e32 v4, v3, v2
	v_cndmask_b32_e32 v3, v3, v4, vcc
	v_add_u32_e32 v4, 1, v1
	v_cmp_ge_u32_e32 vcc, v3, v2
	v_add_u32_e32 v3, 1, v5
	s_nop 0
	v_cndmask_b32_e32 v1, v1, v4, vcc
	v_mul_lo_u32 v4, v2, v1
	v_add_u32_e32 v2, v4, v2
	v_cmp_ne_u32_e32 vcc, v3, v2
	v_readlane_b32 s8, v253, 6
	v_readlane_b32 s9, v253, 7
	s_waitcnt lgkmcnt(0)
	v_add_u32_e32 v4, 1, v1
	v_mul_lo_u32 v4, v4, v0
	s_nop 4
	s_cbranch_vccnz .Lxb_poll
	buffer_wbl2 sc1
	s_waitcnt vmcnt(0)
	v_mov_b32_e32 v5, 1
	global_atomic_add v169, v5, s[8:9]
.Lxb_poll:
	s_mov_b32 s15, 0
.Lxb_spin:
	global_load_dword v5, v169, s[8:9] sc1
	s_waitcnt vmcnt(0)
	v_cmp_ge_u32_e32 vcc, v5, v4
	s_cbranch_vccnz .Lxb_done
	s_sleep 1
	s_add_i32 s15, s15, 1
	s_cmp_lt_u32 s15, 0x40000
	s_cbranch_scc1 .Lxb_spin
.Lxb_done:
.LBB0_79:
	s_or_b64 exec, exec, s[0:1]
	s_waitcnt lgkmcnt(0)
	s_barrier
